# gemm256 entry: previous tile's epilogue stores no longer drained before the first LDS-DMA pieces; stray full drain before the outproj prologue's counted wait removed
# speedup vs baseline: 1.0147x; 1.0014x over previous
; DI int otid() { int t = threadIdx.x; asm volatile("" : "+v"(t)); return t; }
; #define STAGE_A(Pp, br, kt) { const char* g_ = (const char*)(A + (size_t)(br) * lda + (size_t)(kt) * BK); \
;     __builtin_amdgcn_global_load_lds((const unsigned*)(g_ + oa0), (LAS unsigned*)((Pp) + tid * 16), 16, 0, 0); \
;     __builtin_amdgcn_global_load_lds((const unsigned*)(g_ + oa1), (LAS unsigned*)((Pp) + tid * 16 + 8192), 16, 0, 0); }
; #define STAGE_B(Pp, br, kt) { const char* g_ = (const char*)(Bt + (size_t)(br) * ldb + (size_t)(kt) * BK); \
;     __builtin_amdgcn_global_load_lds((const unsigned*)(g_ + ob0), (LAS unsigned*)((Pp) + tid * 16), 16, 0, 0); \
;     __builtin_amdgcn_global_load_lds((const unsigned*)(g_ + ob1), (LAS unsigned*)((Pp) + tid * 16 + 8192), 16, 0, 0); }
; #define WAIT_V(n) asm volatile("s_waitcnt vmcnt(" #n ")" ::: "memory")
; #define BAR8 __builtin_amdgcn_s_barrier()
; template <class Epi>
; DI void gemm256(const bf16_t* __restrict__ A, int lda, const bf16_t* __restrict__ Bt, int ldb, int K, char* lds, Epi epi) {
;   constexpr int BK = 64, HALFR = 128, HTB = HALFR * BK * 2;
;   const int tid = otid();
;   const int wid = tid >> 6, lane = tid & 63, wr = wid >> 2, wc = wid & 3, fr = lane & 15, fq = lane >> 4;
;   const int obs = (fr * 64 + fq * 16) ^ ((((fr * 64 + fq * 16) >> 9) & 1) << 5);
;   const char* lrda = lds + wr * 8192 + obs; const char* lrdb = lds + 4 * HTB + wc * 4096 + obs;
;   int sr0, sc0, sr1, sc1; g8_stage_rc(tid * 16, sr0, sc0); g8_stage_rc(tid * 16 + 8192, sr1, sc1);
;   const unsigned oa0 = (unsigned)(sr0 * lda + sc0) * 2u, oa1 = (unsigned)(sr1 * lda + sc1) * 2u;
;     ...
;   f32x4 acc[2][2][4][2];
; #pragma unroll
;   for (int a = 0; a < 2; ++a)
; #pragma unroll
;     for (int b = 0; b < 2; ++b)
; #pragma unroll
;       for (int m = 0; m < 4; ++m)
; #pragma unroll
;         for (int n = 0; n < 2; ++n) { f32x4 z = {0.f, 0.f, 0.f, 0.f}; acc[a][b][m][n] = z; }
;   bf16x8 At[4][2], B0[2][2], B1[2][2];
;   const int nt = K / BK;
;   WAIT_V(0);
;   __syncthreads();
;   STAGE_B(SB8(0, 0), 0, 0); STAGE_A(SA8(0, 0), 0, 0);
;   STAGE_B(SB8(0, 1), HALFR, 0); STAGE_A(SA8(0, 1), HALFR, 0);
;   if (wr == 1) BAR8;
.LBB0_314:
	s_and_b64 vcc, exec, s[4:5]
	s_cbranch_vccz .LBB0_304
	v_mov_b32_e32 v140, v196
	s_lshl_b32 s4, s20, 8
	v_ashrrev_i32_e32 v0, 31, v140
	v_lshrrev_b32_e32 v0, 26, v0
	v_add_u32_e32 v0, v140, v0
	v_ashrrev_i32_e32 v10, 6, v0
	v_bfe_i32 v0, v140, 27, 1
	v_lshlrev_b32_e32 v13, 4, v140
	v_lshrrev_b32_e32 v0, 22, v0
	v_add_u32_e32 v0, v13, v0
	v_and_b32_e32 v0, 0xfffffc00, v0
	v_sub_u32_e32 v0, v13, v0
	v_lshrrev_b32_e32 v2, 4, v0
	v_bitop3_b32 v2, v2, v0, 32 bitop3:0x6c
	v_ashrrev_i32_e32 v0, 31, v0
	v_lshrrev_b32_e32 v0, 26, v0
	v_add_u32_e32 v0, v2, v0
	v_ashrrev_i32_e32 v11, 6, v0
	v_mul_i32_i24_e32 v4, 64, v11
	v_sub_u32_e32 v2, v2, v4
	v_ashrrev_i16_sdwa v2, v197, sext(v2) dst_sel:DWORD dst_unused:UNUSED_PAD src0_sel:DWORD src1_sel:BYTE_0
	v_bfe_i32 v12, v2, 0, 16
	v_add_u32_e32 v2, 0x2000, v13
	v_ashrrev_i32_e32 v4, 31, v2
	v_lshrrev_b32_e32 v4, 22, v4
	v_add_u32_e32 v4, v2, v4
	v_ashrrev_i32_e32 v14, 10, v4
	v_mul_i32_i24_e32 v4, 0x400, v14
	v_sub_u32_e32 v2, v2, v4
	v_lshrrev_b32_e32 v4, 4, v2
	s_mov_b32 s5, s3
	v_bitop3_b32 v2, v4, v2, 32 bitop3:0x6c
	s_lshl_b32 s2, s2, 8
	s_lshl_b64 s[18:19], s[4:5], 11
	v_ashrrev_i32_e32 v5, 31, v2
	s_add_u32 s46, s50, s18
	v_lshrrev_b32_e32 v5, 26, v5
	s_addc_u32 s47, s51, s19
	s_lshl_b64 s[20:21], s[2:3], 11
	v_add_u32_e32 v5, v2, v5
	s_add_u32 s48, s54, s20
	v_lshlrev_b32_e32 v3, 3, v10
	v_lshlrev_b32_e32 v0, 5, v10
	v_ashrrev_i32_e32 v15, 6, v5
	v_and_b32_e32 v5, 0xc0, v5
	s_addc_u32 s49, s55, s21
	v_and_b32_e32 v3, 0x1ffff0, v3
	v_and_b32_e32 v0, 32, v0
	v_sub_u32_e32 v2, v2, v5
	s_add_i32 s5, 0, 0x10000
	v_add_u32_e32 v0, v0, v12
	v_lshlrev_b32_e32 v4, 3, v14
	v_lshlrev_b32_e32 v6, 5, v14
	v_ashrrev_i16_sdwa v2, v197, sext(v2) dst_sel:DWORD dst_unused:UNUSED_PAD src0_sel:DWORD src1_sel:BYTE_0
	v_add_lshl_u32 v3, v11, v3, 11
	v_add_u32_e32 v148, s5, v13
	v_and_b32_e32 v6, 32, v6
	v_bfe_i32 v16, v2, 0, 16
	v_lshl_add_u32 v0, v0, 1, v3
	v_and_b32_e32 v3, 0x1ffff0, v4
	v_readfirstlane_b32 s34, v148
	v_add_u32_e32 v149, 0x2000, v148
	v_add_u32_e32 v2, v6, v16
	v_add_lshl_u32 v3, v15, v3, 11
	s_mov_b32 m0, s34
	v_readfirstlane_b32 s34, v149
	v_add_u32_e32 v150, 0, v13
	v_lshl_add_u32 v130, v2, 1, v3
	s_barrier
	global_load_lds_dwordx4 v0, s[48:49]
	s_mov_b32 m0, s34
	v_readfirstlane_b32 s34, v150
	v_add_u32_e32 v151, 0x2000, v150
	v_readlane_b32 s64, v255, 20
	global_load_lds_dwordx4 v130, s[48:49]
	s_mov_b32 m0, s34
	v_readfirstlane_b32 s34, v151
	v_add_u32_e32 v152, s64, v13
	global_load_lds_dwordx4 v0, s[46:47]
	s_mov_b32 m0, s34
	s_add_u32 s34, s48, 0x40000
	v_readfirstlane_b32 s64, v152
	v_add_u32_e32 v153, 0x2000, v152
	global_load_lds_dwordx4 v130, s[46:47]
	s_addc_u32 s35, s49, 0
	s_mov_b32 m0, s64
	v_readfirstlane_b32 s64, v153
	global_load_lds_dwordx4 v0, s[34:35]
	s_mov_b32 m0, s64
	v_add_u32_e32 v154, 0x4000, v150
	global_load_lds_dwordx4 v130, s[34:35]
	s_add_u32 s34, s46, 0x40000
	v_readfirstlane_b32 s64, v154
	v_add_u32_e32 v155, 0x6000, v150
	s_addc_u32 s35, s47, 0
	s_mov_b32 m0, s64
	v_readfirstlane_b32 s64, v155
	global_load_lds_dwordx4 v0, s[34:35]
	s_mov_b32 m0, s64
	v_ashrrev_i32_e32 v141, 8, v140
	global_load_lds_dwordx4 v130, s[34:35]
	v_mov_b32_e32 v131, v1
	v_lshl_add_u64 v[8:9], s[48:49], 0, v[0:1]
	v_lshl_add_u64 v[6:7], s[48:49], 0, v[130:131]
	v_lshl_add_u64 v[4:5], s[46:47], 0, v[0:1]
	v_lshl_add_u64 v[2:3], s[46:47], 0, v[130:131]
	v_cmp_eq_u32_e32 vcc, 1, v141
	s_and_saveexec_b64 s[34:35], vcc
	s_cbranch_execz .LBB0_317
	s_barrier

; DI int otid() { int t = threadIdx.x; asm volatile("" : "+v"(t)); return t; }
; #define STAGE_A(Pp, br, kt) { const char* g_ = (const char*)(A + (size_t)(br) * lda + (size_t)(kt) * BK); \
;     __builtin_amdgcn_global_load_lds((const unsigned*)(g_ + oa0), (LAS unsigned*)((Pp) + tid * 16), 16, 0, 0); \
;     __builtin_amdgcn_global_load_lds((const unsigned*)(g_ + oa1), (LAS unsigned*)((Pp) + tid * 16 + 8192), 16, 0, 0); }
; #define WAIT_V(n) asm volatile("s_waitcnt vmcnt(" #n ")" ::: "memory")
; #define BAR8 __builtin_amdgcn_s_barrier()
; template <class Epi>
; DI void gemm256(const bf16_t* __restrict__ A, int lda, const bf16_t* __restrict__ Bt, int ldb, int K, char* lds, Epi epi) {
;     ...
;   const int tid = otid();
;   const int wid = tid >> 6, lane = tid & 63, wr = wid >> 2, wc = wid & 3, fr = lane & 15, fq = lane >> 4;
;   const int obs = (fr * 64 + fq * 16) ^ ((((fr * 64 + fq * 16) >> 9) & 1) << 5);
;   const char* lrda = lds + wr * 8192 + obs; const char* lrdb = lds + 4 * HTB + wc * 4096 + obs;
;   int sr0, sc0, sr1, sc1; g8_stage_rc(tid * 16, sr0, sc0); g8_stage_rc(tid * 16 + 8192, sr1, sc1);
;   const unsigned oa0 = (unsigned)(sr0 * lda + sc0) * 2u, oa1 = (unsigned)(sr1 * lda + sc1) * 2u;
;     ...
;   f32x4 acc[2][2][4][2];
; #pragma unroll
;   for (int a = 0; a < 2; ++a)
; #pragma unroll
;     for (int b = 0; b < 2; ++b)
; #pragma unroll
;       for (int m = 0; m < 4; ++m)
; #pragma unroll
;         for (int n = 0; n < 2; ++n) { f32x4 z = {0.f, 0.f, 0.f, 0.f}; acc[a][b][m][n] = z; }
;   bf16x8 At[4][2], B0[2][2], B1[2][2];
;   const int nt = K / BK;
;   WAIT_V(0);
;   __syncthreads();
;   STAGE_B(SB8(0, 0), 0, 0); STAGE_A(SA8(0, 0), 0, 0);
;   STAGE_B(SB8(0, 1), HALFR, 0); STAGE_A(SA8(0, 1), HALFR, 0);
;   if (wr == 1) BAR8;
; DI void phase_outproj(KP p, int l, char* lds) {
;     ...
;       const int mi = j >> 2, nt = j & 3;
;       const int bb = 2 * xcd + (mi >> 3), tt = mi & 7;
;       const int m0 = (bb * 9 + tt) * 256, n0 = nt * 256;
;       const float* src = xl + ((size_t)bb * SEQ + tt * 256) * 1024;
;       float* dst = p->out + ((size_t)bb * SEQ + tt * 256) * 1024;
;       const float* gt = mod + (size_t)bb * 3072 + 2048;
;       gemm256(Y + (size_t)m0 * 1024, 1024, wo + (size_t)n0 * 1024, 1024, 1024, lds, [&](int m, int n, f32x4 v) {
.LBB0_343:
	v_mov_b32_e32 v140, v196
	s_lshr_b32 s2, s64, 5
	v_ashrrev_i32_e32 v0, 31, v140
	v_lshrrev_b32_e32 v0, 26, v0
	v_add_u32_e32 v0, v140, v0
	v_ashrrev_i32_e32 v10, 6, v0
	v_bfe_i32 v0, v140, 27, 1
	v_lshlrev_b32_e32 v13, 4, v140
	v_lshrrev_b32_e32 v0, 22, v0
	v_add_u32_e32 v0, v13, v0
	v_and_b32_e32 v0, 0xfffffc00, v0
	v_sub_u32_e32 v0, v13, v0
	v_lshrrev_b32_e32 v2, 4, v0
	v_bitop3_b32 v2, v2, v0, 32 bitop3:0x6c
	v_ashrrev_i32_e32 v0, 31, v0
	v_lshrrev_b32_e32 v0, 26, v0
	v_add_u32_e32 v0, v2, v0
	v_ashrrev_i32_e32 v11, 6, v0
	v_mul_i32_i24_e32 v4, 64, v11
	v_sub_u32_e32 v2, v2, v4
	v_ashrrev_i16_sdwa v2, v197, sext(v2) dst_sel:DWORD dst_unused:UNUSED_PAD src0_sel:DWORD src1_sel:BYTE_0
	v_bfe_i32 v12, v2, 0, 16
	v_add_u32_e32 v2, 0x2000, v13
	v_ashrrev_i32_e32 v4, 31, v2
	v_lshrrev_b32_e32 v4, 22, v4
	v_add_u32_e32 v4, v2, v4
	v_ashrrev_i32_e32 v14, 10, v4
	v_readlane_b32 s4, v253, 5
	v_mul_i32_i24_e32 v4, 0x400, v14
	s_add_i32 s4, s2, s4
	v_sub_u32_e32 v2, v2, v4
	s_bfe_u32 s50, s64, 0x30002
	s_mul_i32 s5, s4, 9
	v_lshrrev_b32_e32 v4, 4, v2
	s_add_i32 s5, s5, s50
	s_lshl_b32 s18, s64, 8
	v_bitop3_b32 v2, v4, v2, 32 bitop3:0x6c
	s_and_b32 s65, s18, 0x300
	s_lshl_b32 s5, s5, 19
	v_ashrrev_i32_e32 v5, 31, v2
	s_add_u32 s48, s34, s5
	v_lshrrev_b32_e32 v5, 26, v5
	s_addc_u32 s49, s35, 0
	s_lshl_b32 s5, s65, 11
	v_add_u32_e32 v5, v2, v5
	s_add_u32 s18, s52, s5
	v_lshlrev_b32_e32 v3, 3, v10
	v_lshlrev_b32_e32 v0, 5, v10
	v_ashrrev_i32_e32 v15, 6, v5
	v_and_b32_e32 v5, 0xc0, v5
	s_addc_u32 s19, s53, 0
	v_and_b32_e32 v3, 0x1ffff0, v3
	v_and_b32_e32 v0, 32, v0
	v_sub_u32_e32 v2, v2, v5
	s_add_i32 s5, 0, 0x10000
	v_add_u32_e32 v0, v0, v12
	v_lshlrev_b32_e32 v4, 3, v14
	v_lshlrev_b32_e32 v6, 5, v14
	v_ashrrev_i16_sdwa v2, v197, sext(v2) dst_sel:DWORD dst_unused:UNUSED_PAD src0_sel:DWORD src1_sel:BYTE_0
	v_add_lshl_u32 v3, v11, v3, 11
	v_add_u32_e32 v148, s5, v13
	v_and_b32_e32 v6, 32, v6
	v_bfe_i32 v16, v2, 0, 16
	v_lshl_add_u32 v0, v0, 1, v3
	v_and_b32_e32 v3, 0x1ffff0, v4
	v_readfirstlane_b32 s20, v148
	v_add_u32_e32 v149, 0x2000, v148
	v_add_u32_e32 v2, v6, v16
	v_add_lshl_u32 v3, v15, v3, 11
	s_mov_b32 m0, s20
	v_readfirstlane_b32 s20, v149
	v_add_u32_e32 v150, 0, v13
	v_lshl_add_u32 v130, v2, 1, v3
	s_waitcnt lgkmcnt(0)
	s_barrier
	global_load_lds_dwordx4 v0, s[18:19]
	s_mov_b32 m0, s20
	v_readfirstlane_b32 s20, v150
	v_add_u32_e32 v151, 0x2000, v150
	v_readlane_b32 s51, v255, 20
	global_load_lds_dwordx4 v130, s[18:19]
	s_mov_b32 m0, s20
	v_readfirstlane_b32 s20, v151
	v_add_u32_e32 v152, s51, v13
	global_load_lds_dwordx4 v0, s[48:49]
	s_mov_b32 m0, s20
	s_add_u32 s20, s18, 0x40000
	v_readfirstlane_b32 s51, v152
	v_add_u32_e32 v153, 0x2000, v152
	global_load_lds_dwordx4 v130, s[48:49]
	s_addc_u32 s21, s19, 0
	s_mov_b32 m0, s51
	v_readfirstlane_b32 s51, v153
	global_load_lds_dwordx4 v0, s[20:21]
	s_mov_b32 m0, s51
	v_add_u32_e32 v154, 0x4000, v150
	global_load_lds_dwordx4 v130, s[20:21]
	s_add_u32 s20, s48, 0x40000
	v_readfirstlane_b32 s51, v154
	v_add_u32_e32 v155, 0x6000, v150
	s_addc_u32 s21, s49, 0
	s_mov_b32 m0, s51
	v_readfirstlane_b32 s51, v155
	global_load_lds_dwordx4 v0, s[20:21]
	s_mov_b32 m0, s51
	v_ashrrev_i32_e32 v141, 8, v140
	global_load_lds_dwordx4 v130, s[20:21]
	v_mov_b32_e32 v131, v1
	v_lshl_add_u64 v[8:9], s[18:19], 0, v[0:1]
	v_lshl_add_u64 v[6:7], s[18:19], 0, v[130:131]
	v_lshl_add_u64 v[4:5], s[48:49], 0, v[0:1]
	v_lshl_add_u64 v[2:3], s[48:49], 0, v[130:131]
	v_cmp_eq_u32_e32 vcc, 1, v141
	s_and_saveexec_b64 s[20:21], vcc
	s_cbranch_execz .LBB0_345
	s_barrier
; #define STAGE_A(Pp, br, kt) { const char* g_ = (const char*)(A + (size_t)(br) * lda + (size_t)(kt) * BK); \
;     __builtin_amdgcn_global_load_lds((const unsigned*)(g_ + oa0), (LAS unsigned*)((Pp) + tid * 16), 16, 0, 0); \
;     __builtin_amdgcn_global_load_lds((const unsigned*)(g_ + oa1), (LAS unsigned*)((Pp) + tid * 16 + 8192), 16, 0, 0); }
; #define STAGE_B(Pp, br, kt) { const char* g_ = (const char*)(Bt + (size_t)(br) * ldb + (size_t)(kt) * BK); \
;     __builtin_amdgcn_global_load_lds((const unsigned*)(g_ + ob0), (LAS unsigned*)((Pp) + tid * 16), 16, 0, 0); \
;     __builtin_amdgcn_global_load_lds((const unsigned*)(g_ + ob1), (LAS unsigned*)((Pp) + tid * 16 + 8192), 16, 0, 0); }
; #define WAIT_V(n) asm volatile("s_waitcnt vmcnt(" #n ")" ::: "memory")
; #define BAR8 __builtin_amdgcn_s_barrier()
; template <class Epi>
; DI void gemm256(const bf16_t* __restrict__ A, int lda, const bf16_t* __restrict__ Bt, int ldb, int K, char* lds, Epi epi) {
;     ...
;   f32x4 acc[2][2][4][2];
; #pragma unroll
;   for (int a = 0; a < 2; ++a)
; #pragma unroll
;     for (int b = 0; b < 2; ++b)
; #pragma unroll
;       for (int m = 0; m < 4; ++m)
; #pragma unroll
;         for (int n = 0; n < 2; ++n) { f32x4 z = {0.f, 0.f, 0.f, 0.f}; acc[a][b][m][n] = z; }
;   bf16x8 At[4][2], B0[2][2], B1[2][2];
;   const int nt = K / BK;
;   WAIT_V(0);
;   __syncthreads();
;   STAGE_B(SB8(0, 0), 0, 0); STAGE_A(SA8(0, 0), 0, 0);
;   STAGE_B(SB8(0, 1), HALFR, 0); STAGE_A(SA8(0, 1), HALFR, 0);
;   if (wr == 1) BAR8;
;   WAIT_V(4); BAR8;
;   STAGE_B(SB8(1, 0), 0, 1); STAGE_A(SA8(1, 0), 0, 1); STAGE_B(SB8(1, 1), HALFR, 1);
;   WAIT_V(6); BAR8;
.LBB0_345:
	s_or_b64 exec, exec, s[20:21]
	v_bfe_u32 v142, v140, 6, 2
	v_lshl_add_u32 v20, v142, 12, s5
	v_readlane_b32 s5, v255, 21
	s_lshr_b32 s20, s64, 2
	s_mul_i32 s2, s2, 9
	v_readlane_b32 s21, v255, 11
	v_add_u32_e32 v156, s5, v13
	s_add_i32 s2, s21, s2
	s_and_b32 s20, s20, 7
	v_readfirstlane_b32 s5, v156
	v_add_u32_e32 v157, 0x2000, v156
	s_add_i32 s2, s2, s20
	v_lshl_add_u64 v[8:9], v[8:9], 0, s[28:29]
	s_mov_b32 m0, s5
	v_readfirstlane_b32 s5, v157
	v_add_u32_e32 v158, 0x8000, v150
	s_lshl_b32 s2, s2, 18
	s_waitcnt vmcnt(4)
	s_barrier
	global_load_lds_dwordx4 v[8:9], off
	v_lshl_add_u64 v[6:7], v[6:7], 0, s[28:29]
	s_mov_b32 m0, s5
	v_readfirstlane_b32 s5, v158
	v_add_u32_e32 v159, 0xa000, v150
	s_lshl_b64 s[20:21], s[2:3], 1
	s_lshl_b32 s2, s57, 11
	global_load_lds_dwordx4 v[6:7], off
	v_lshl_add_u64 v[4:5], v[4:5], 0, s[28:29]
	s_mov_b32 m0, s5
	v_readfirstlane_b32 s5, v159
	s_and_b32 s2, s2, 0x180000
	global_load_lds_dwordx4 v[4:5], off
	s_mov_b32 m0, s5
	v_readlane_b32 s5, v255, 22
	s_add_u32 s18, s18, 0x40080
	v_lshl_add_u64 v[2:3], v[2:3], 0, s[28:29]
	v_add_u32_e32 v160, s5, v13
	s_addc_u32 s19, s19, 0
	v_readfirstlane_b32 s5, v160
	v_add_u32_e32 v161, 0x2000, v160
	global_load_lds_dwordx4 v[2:3], off
	v_lshl_add_u64 v[2:3], s[18:19], 0, v[0:1]
	s_mov_b32 m0, s5
	v_readfirstlane_b32 s5, v161
	global_load_lds_dwordx4 v[2:3], off
	v_lshl_add_u64 v[2:3], s[18:19], 0, v[130:131]
	s_mov_b32 m0, s5
	v_lshlrev_b32_e32 v4, 14, v10
	global_load_lds_dwordx4 v[2:3], off
	v_lshlrev_b32_e32 v2, 14, v14
	v_and_b32_e32 v2, 0xffff8000, v2
	v_lshl_add_u32 v2, v15, 11, v2
	v_and_b32_e32 v3, 1, v14
	v_and_b32_e32 v4, 0xffff8000, v4
	v_bfe_u32 v144, v140, 4, 2
	v_lshlrev_b32_e32 v143, 2, v140
	v_and_b32_e32 v145, 15, v140
	v_lshl_or_b32 v2, v3, 6, v2
	v_lshl_add_u32 v4, v11, 11, v4
	v_and_b32_e32 v5, 1, v10
	s_add_u32 s18, s40, s2
	v_lshlrev_b32_e32 v17, 4, v144
	v_and_b32_e32 v18, 32, v143
	v_lshlrev_b32_e32 v21, 6, v145
	s_waitcnt vmcnt(6)
	v_lshl_add_u32 v2, v16, 1, v2
	v_mov_b32_e32 v3, v1
	v_lshl_or_b32 v4, v5, 6, v4
	s_addc_u32 s19, s41, 0
	v_lshl_add_u32 v19, v141, 13, 0
	v_bitop3_b32 v17, v17, v18, v21 bitop3:0x36
	v_lshl_add_u64 v[132:133], s[20:21], 0, v[2:3]
	v_lshl_add_u32 v4, v12, 1, v4
	v_mov_b32_e32 v5, v1
	v_lshl_add_u64 v[136:137], s[18:19], 0, v[2:3]
	v_mov_b32_e32 v2, 0
	v_lshl_add_u64 v[134:135], s[20:21], 0, v[4:5]
	v_lshl_add_u64 v[138:139], s[18:19], 0, v[4:5]
	s_mov_b32 s2, -2
	v_add_u32_e32 v147, v20, v17
	v_add_u32_e32 v146, v19, v17
	v_mov_b32_e32 v3, v2
	v_mov_b32_e32 v4, v2
	v_mov_b32_e32 v5, v2
	v_mov_b32_e32 v6, v2
	v_mov_b32_e32 v7, v2
	v_mov_b32_e32 v8, v2
	v_mov_b32_e32 v9, v2
	v_mov_b32_e32 v10, v2
	v_mov_b32_e32 v11, v2
	v_mov_b32_e32 v12, v2
	v_mov_b32_e32 v13, v2
	v_mov_b32_e32 v14, v2
	v_mov_b32_e32 v15, v2
	v_mov_b32_e32 v16, v2
	v_mov_b32_e32 v17, v2
	v_mov_b32_e32 v18, v2
	v_mov_b32_e32 v19, v2
	v_mov_b32_e32 v20, v2
	v_mov_b32_e32 v21, v2
	v_mov_b32_e32 v22, v2
	v_mov_b32_e32 v23, v2
	v_mov_b32_e32 v24, v2
	v_mov_b32_e32 v25, v2
	v_mov_b32_e32 v26, v2
	v_mov_b32_e32 v27, v2
	v_mov_b32_e32 v28, v2
	v_mov_b32_e32 v29, v2
	v_mov_b32_e32 v30, v2
	v_mov_b32_e32 v31, v2
	v_mov_b32_e32 v32, v2
	v_mov_b32_e32 v33, v2
	v_mov_b32_e32 v34, v2
	v_mov_b32_e32 v35, v2
	v_mov_b32_e32 v36, v2
	v_mov_b32_e32 v37, v2
	v_mov_b32_e32 v38, v2
	v_mov_b32_e32 v39, v2
	v_mov_b32_e32 v40, v2
	v_mov_b32_e32 v41, v2
	v_mov_b32_e32 v42, v2
	v_mov_b32_e32 v43, v2
	v_mov_b32_e32 v44, v2
	v_mov_b32_e32 v45, v2
	v_mov_b32_e32 v46, v2
	v_mov_b32_e32 v47, v2
	v_mov_b32_e32 v48, v2
	v_mov_b32_e32 v49, v2
	v_mov_b32_e32 v50, v2
	v_mov_b32_e32 v51, v2
	v_mov_b32_e32 v52, v2
	v_mov_b32_e32 v53, v2
	v_mov_b32_e32 v54, v2
	v_mov_b32_e32 v55, v2
	v_mov_b32_e32 v56, v2
	v_mov_b32_e32 v57, v2
	v_mov_b32_e32 v58, v2
	v_mov_b32_e32 v59, v2
	v_mov_b32_e32 v60, v2
	v_mov_b32_e32 v61, v2
	v_mov_b32_e32 v62, v2
	v_mov_b32_e32 v63, v2
	v_mov_b32_e32 v64, v2
	v_mov_b32_e32 v65, v2
	v_mov_b32_e32 v66, v2
	v_mov_b32_e32 v67, v2
	v_mov_b32_e32 v68, v2
	v_mov_b32_e32 v69, v2
	v_mov_b32_e32 v70, v2
	v_mov_b32_e32 v71, v2
	v_mov_b32_e32 v72, v2
	v_mov_b32_e32 v73, v2
	v_mov_b32_e32 v74, v2
	v_mov_b32_e32 v75, v2
	v_mov_b32_e32 v76, v2
	v_mov_b32_e32 v77, v2
	v_mov_b32_e32 v78, v2
	v_mov_b32_e32 v79, v2
	v_mov_b32_e32 v80, v2
	v_mov_b32_e32 v81, v2
	v_mov_b32_e32 v82, v2
	v_mov_b32_e32 v83, v2
	v_mov_b32_e32 v84, v2
	v_mov_b32_e32 v85, v2
	v_mov_b32_e32 v86, v2
	v_mov_b32_e32 v87, v2
	v_mov_b32_e32 v88, v2
	v_mov_b32_e32 v89, v2
	v_mov_b32_e32 v90, v2
	v_mov_b32_e32 v91, v2
	v_mov_b32_e32 v92, v2
	v_mov_b32_e32 v93, v2
	v_mov_b32_e32 v94, v2
	v_mov_b32_e32 v95, v2
	v_mov_b32_e32 v96, v2
	v_mov_b32_e32 v97, v2
	v_mov_b32_e32 v98, v2
	v_mov_b32_e32 v99, v2
	v_mov_b32_e32 v100, v2
	v_mov_b32_e32 v101, v2
	v_mov_b32_e32 v102, v2
	v_mov_b32_e32 v103, v2
	v_mov_b32_e32 v104, v2
	v_mov_b32_e32 v105, v2
	v_mov_b32_e32 v106, v2
	v_mov_b32_e32 v107, v2
	v_mov_b32_e32 v108, v2
	v_mov_b32_e32 v109, v2
	v_mov_b32_e32 v110, v2
	v_mov_b32_e32 v111, v2
	v_mov_b32_e32 v112, v2
	v_mov_b32_e32 v113, v2
	v_mov_b32_e32 v114, v2
	v_mov_b32_e32 v115, v2
	v_mov_b32_e32 v116, v2
	v_mov_b32_e32 v117, v2
	v_mov_b32_e32 v118, v2
	v_mov_b32_e32 v119, v2
	v_mov_b32_e32 v120, v2
	v_mov_b32_e32 v121, v2
	v_mov_b32_e32 v122, v2
	v_mov_b32_e32 v123, v2
	v_mov_b32_e32 v124, v2
	v_mov_b32_e32 v125, v2
	v_mov_b32_e32 v126, v2
	v_mov_b32_e32 v127, v2
	v_mov_b32_e32 v128, v2
	v_mov_b32_e32 v129, v2
	s_barrier
